# k10 + XCD-level start stagger of the out/up/down projection GEMM phases: XCC x sleeps x*896 cycles so the per-unit epilogue store bursts of the 8 XCDs do not coincide
# baseline (speedup 1.0000x reference)
.LBB0_741:
	s_mov_b64 s[44:45], 0x80
	s_bfe_u32 s42, s33, 0x20006
	s_add_i32 m0, s68, 0x18000
	v_lshl_add_u64 v[6:7], v[6:7], 0, s[44:45]
	s_lshl_b32 s5, s4, 13
	s_lshl_b32 s14, s42, 12
	s_waitcnt vmcnt(2)
	s_barrier
	global_load_lds_dwordx4 v[6:7], off
	v_lshl_add_u64 v[4:5], v[4:5], 0, s[44:45]
	s_add_i32 m0, s68, 0x1a000
	s_add_i32 s72, s68, 0x8000
	s_add_i32 s73, s68, 0xa000
	global_load_lds_dwordx4 v[4:5], off
	v_lshl_add_u64 v[0:1], v[0:1], 0, s[44:45]
	s_mov_b32 m0, s72
	s_add_u32 s6, s64, 0x100080
	global_load_lds_dwordx4 v[0:1], off
	v_lshl_add_u64 v[0:1], v[2:3], 0, s[44:45]
	s_mov_b32 m0, s73
	s_addc_u32 s7, s65, 0
	global_load_lds_dwordx4 v[0:1], off
	s_add_i32 m0, s68, 0x1c000
	v_lshl_add_u64 v[0:1], s[6:7], 0, v[146:147]
	global_load_lds_dwordx4 v[0:1], off
	v_lshl_add_u64 v[0:1], s[6:7], 0, v[150:151]
	s_add_i32 m0, s68, 0x1e000
	v_lshlrev_b32_e32 v4, 2, v9
	global_load_lds_dwordx4 v[0:1], off
	v_and_b32_e32 v0, 15, v9
	v_lshl_or_b32 v174, s4, 6, v0
	v_and_b32_e32 v2, 48, v9
	v_lshlrev_b32_e32 v0, 6, v0
	v_and_b32_e32 v5, 32, v4
	v_and_b32_e32 v3, 0x400, v12
	v_bitop3_b32 v0, v0, v5, v2 bitop3:0x36
	v_lshrrev_b32_e32 v1, 1, v9
	v_or3_b32 v2, v3, s5, v0
	v_or3_b32 v175, v3, s14, v0
	v_lshlrev_b32_e32 v0, 16, v8
	v_and_b32_e32 v1, 56, v1
	v_and_b32_e32 v0, 0xfffe0000, v0
	v_lshl_add_u32 v176, s42, 5, v1
	v_lshl_add_u32 v0, v10, 13, v0
	v_and_b32_e32 v1, 1, v8
	v_lshl_or_b32 v0, v1, 6, v0
	v_lshl_add_u32 v154, v11, 1, v0
	v_lshlrev_b32_e32 v0, 16, v13
	v_and_b32_e32 v0, 0xfffe0000, v0
	s_waitcnt vmcnt(6)
	s_cmpk_lt_u32 s33, 0x100
	v_lshl_add_u32 v0, v14, 13, v0
	v_and_b32_e32 v1, 1, v13
	s_cselect_b64 s[46:47], -1, 0
	v_lshl_or_b32 v0, v1, 6, v0
	s_add_i32 s75, 0, 0x10000
	s_add_i32 s76, 0, 0x14000
	v_cmp_gt_u32_e64 s[6:7], 16, v9
	s_mov_b32 s43, s39
	v_xor_b32_e32 v177, 64, v4
	v_xor_b32_e32 v178, 0x80, v4
	s_ashr_i32 s74, s2, 31
	v_mov_b32_e32 v155, v152
	v_lshl_add_u32 v156, v15, 1, v0
	v_mov_b32_e32 v157, v152
	v_mov_b64_e32 v[158:159], 0x400
	v_mov_b64_e32 v[160:161], 0x3ff
	v_add_u32_e32 v179, s75, v175
	v_add_u32_e32 v180, s76, v175
	v_add_u32_e32 v181, 0, v2
	s_mov_b32 s48, 0x3f9837f0
	s_mov_b32 s38, s39
	s_barrier
	s_getreg_b32 s52, hwreg(HW_REG_XCC_ID, 0, 4)
	s_and_b32 s52, s52, 7
.Lstg_744:
	s_cmp_eq_u32 s52, 0
	s_cbranch_scc1 .Lstg_done_744
	s_sleep 14
	s_sub_u32 s52, s52, 1
	s_branch .Lstg_744
.Lstg_done_744:
	s_branch .LBB0_744

.LBB0_830:
	s_lshl_b32 s14, s3, 5
	s_mov_b64 s[30:31], 0x80
	s_and_b32 s36, s14, 0x60
	s_add_i32 m0, s53, 0x18000
	v_lshl_add_u64 v[6:7], v[6:7], 0, s[30:31]
	s_lshl_b32 s24, s5, 13
	s_lshr_b32 s34, s36, 3
	s_waitcnt vmcnt(2)
	s_barrier
	global_load_lds_dwordx4 v[6:7], off
	v_lshl_add_u64 v[4:5], v[4:5], 0, s[30:31]
	s_add_i32 m0, s53, 0x1a000
	s_add_i32 s65, s53, 0x8000
	s_add_i32 s66, s53, 0xa000
	global_load_lds_dwordx4 v[4:5], off
	v_lshl_add_u64 v[0:1], v[0:1], 0, s[30:31]
	s_mov_b32 m0, s65
	s_add_u32 s14, s56, 0x100080
	global_load_lds_dwordx4 v[0:1], off
	v_lshl_add_u64 v[0:1], v[2:3], 0, s[30:31]
	s_mov_b32 m0, s66
	s_addc_u32 s15, s57, 0
	global_load_lds_dwordx4 v[0:1], off
	s_add_i32 m0, s53, 0x1c000
	v_lshl_add_u64 v[0:1], s[14:15], 0, v[162:163]
	global_load_lds_dwordx4 v[0:1], off
	v_lshl_add_u64 v[0:1], s[14:15], 0, v[166:167]
	s_add_i32 m0, s53, 0x1e000
	v_lshrrev_b32_e32 v2, 6, v9
	global_load_lds_dwordx4 v[0:1], off
	v_lshrrev_b32_e32 v1, 1, v9
	v_and_b32_e32 v0, 15, v9
	v_and_b32_e32 v1, 56, v1
	v_lshlrev_b32_e32 v5, 2, v9
	v_lshl_or_b32 v180, s5, 6, v0
	v_and_b32_e32 v3, 48, v9
	v_lshlrev_b32_e32 v4, 10, v2
	v_lshlrev_b32_e32 v0, 6, v0
	v_and_b32_e32 v5, 32, v5
	v_or_b32_e32 v2, s34, v2
	v_add_u32_e32 v182, s36, v1
	v_lshlrev_b32_e32 v1, 16, v8
	v_bitop3_b32 v6, v0, v5, v3 bitop3:0x36
	v_or_b32_e32 v0, v0, v3
	v_lshlrev_b32_e32 v2, 10, v2
	v_and_b32_e32 v1, 0xfffe0000, v1
	v_bitop3_b32 v181, v0, v2, v5 bitop3:0xde
	v_lshl_add_u32 v1, v10, 13, v1
	v_and_b32_e32 v2, 1, v8
	v_lshl_or_b32 v1, v2, 6, v1
	v_lshl_add_u32 v168, v11, 1, v1
	v_lshlrev_b32_e32 v1, 16, v12
	v_and_b32_e32 v1, 0xfffe0000, v1
	s_waitcnt vmcnt(6)
	s_cmpk_lt_u32 s33, 0x100
	v_lshlrev_b32_e32 v0, 3, v180
	v_lshl_add_u32 v1, v13, 13, v1
	v_and_b32_e32 v2, 1, v12
	v_or3_b32 v4, v4, s24, v6
	s_cselect_b64 s[34:35], -1, 0
	v_lshl_or_b32 v1, v2, 6, v1
	s_add_i32 s67, 0, 0x10000
	s_add_i32 s68, 0, 0x14000
	v_add_u32_e32 v0, 0, v0
	s_sext_i32_i16 s73, s4
	v_mov_b32_e32 v169, v163
	v_lshl_add_u32 v170, v14, 1, v1
	v_mov_b32_e32 v171, v163
	v_mov_b64_e32 v[172:173], 0x1000
	v_mov_b64_e32 v[174:175], 0xfff
	v_add_u32_e32 v183, s67, v181
	v_add_u32_e32 v184, s68, v181
	v_add_u32_e32 v185, 0, v4
	v_add_u32_e32 v186, 0x21000, v0
	s_mov_b64 s[36:37], 0x400000
	s_mov_b32 s69, 0x400000
	s_mov_b64 s[38:39], 0x480000
	s_mov_b32 s70, 0x480000
	s_mov_b64 s[40:41], 0x500000
	s_mov_b32 s71, 0x500000
	s_mov_b64 s[42:43], 0x580000
	s_mov_b32 s72, 0x580000
	s_mov_b32 s24, s25
	s_barrier
	s_getreg_b32 s46, hwreg(HW_REG_XCC_ID, 0, 4)
	s_and_b32 s46, s46, 7
.Lstg_833:
	s_cmp_eq_u32 s46, 0
	s_cbranch_scc1 .Lstg_done_833
	s_sleep 14
	s_sub_u32 s46, s46, 1
	s_branch .Lstg_833

.LBB0_877:
	s_add_u32 s28, s16, 0x2000
	s_addc_u32 s29, s17, 0
	s_lshl_b32 s4, s3, 5
	s_mov_b64 s[30:31], 0x80
	s_and_b32 s15, s4, 0x60
	s_add_i32 m0, s47, 0x18000
	v_lshl_add_u64 v[6:7], v[6:7], 0, s[30:31]
	s_lshl_b32 s14, s35, 13
	s_lshr_b32 s24, s15, 3
	s_waitcnt vmcnt(2)
	s_barrier
	global_load_lds_dwordx4 v[6:7], off
	v_lshl_add_u64 v[4:5], v[4:5], 0, s[30:31]
	s_add_i32 m0, s47, 0x1a000
	s_add_i32 s58, s47, 0x8000
	s_add_i32 s59, s47, 0xa000
	global_load_lds_dwordx4 v[4:5], off
	v_lshl_add_u64 v[0:1], v[0:1], 0, s[30:31]
	s_mov_b32 m0, s58
	s_add_u32 s4, s50, 0x400080
	global_load_lds_dwordx4 v[0:1], off
	v_lshl_add_u64 v[0:1], v[2:3], 0, s[30:31]
	s_mov_b32 m0, s59
	s_addc_u32 s5, s51, 0
	global_load_lds_dwordx4 v[0:1], off
	s_add_i32 m0, s47, 0x1c000
	v_lshl_add_u64 v[0:1], s[4:5], 0, v[146:147]
	global_load_lds_dwordx4 v[0:1], off
	v_lshl_add_u64 v[0:1], s[4:5], 0, v[150:151]
	s_add_i32 m0, s47, 0x1e000
	v_lshrrev_b32_e32 v2, 6, v9
	global_load_lds_dwordx4 v[0:1], off
	v_and_b32_e32 v0, 15, v9
	v_lshlrev_b32_e32 v5, 2, v9
	v_lshl_or_b32 v172, s35, 6, v0
	v_and_b32_e32 v3, 48, v9
	v_lshlrev_b32_e32 v4, 10, v2
	v_lshlrev_b32_e32 v0, 6, v0
	v_and_b32_e32 v5, 32, v5
	v_or_b32_e32 v2, s24, v2
	v_bitop3_b32 v6, v0, v5, v3 bitop3:0x36
	v_or_b32_e32 v0, v0, v3
	v_lshlrev_b32_e32 v2, 10, v2
	v_lshrrev_b32_e32 v1, 1, v9
	v_bitop3_b32 v173, v0, v2, v5 bitop3:0xde
	v_lshlrev_b32_e32 v0, 18, v8
	v_and_b32_e32 v1, 56, v1
	v_and_b32_e32 v0, 0xfff80000, v0
	v_add_u32_e32 v174, s15, v1
	v_lshl_add_u32 v0, v10, 15, v0
	v_and_b32_e32 v1, 1, v8
	v_lshl_or_b32 v0, v1, 6, v0
	v_lshl_add_u32 v152, v11, 1, v0
	v_lshlrev_b32_e32 v0, 18, v12
	v_and_b32_e32 v0, 0xfff80000, v0
	s_waitcnt vmcnt(6)
	s_cmpk_lt_u32 s33, 0x100
	v_lshl_add_u32 v0, v13, 15, v0
	v_and_b32_e32 v1, 1, v12
	s_sext_i32_i8 s61, s34
	v_or3_b32 v4, v4, s14, v6
	s_cselect_b64 s[34:35], -1, 0
	v_lshl_or_b32 v0, v1, 6, v0
	s_add_i32 s33, 0, 0x10000
	s_add_i32 s60, 0, 0x14000
	v_mov_b32_e32 v153, v147
	v_lshl_add_u32 v154, v14, 1, v0
	v_mov_b32_e32 v155, v147
	v_mov_b64_e32 v[156:157], 0x400
	v_mov_b64_e32 v[158:159], 0x3ff
	v_add_u32_e32 v175, s33, v173
	v_add_u32_e32 v176, s60, v173
	v_add_u32_e32 v177, 0, v4
	s_mov_b32 s36, 0x3f9837f0
	s_mov_b32 s24, s25
	s_barrier
	s_getreg_b32 s40, hwreg(HW_REG_XCC_ID, 0, 4)
	s_and_b32 s40, s40, 7
.Lstg_880:
	s_cmp_eq_u32 s40, 0
	s_cbranch_scc1 .Lstg_done_880
	s_sleep 14
	s_sub_u32 s40, s40, 1
	s_branch .Lstg_880
